# differential attention: K fragment LDS reads of the 4th sub-tile body issued together (counted lgkmcnt), completing the fragment prefetch in all four bodies (on v109)
# baseline (speedup 1.0000x reference)
.LBB0_380:
	ds_read_b128 v[6:9], v4
	ds_read_b128 v[10:13], v5
	ds_read_b128 v[132:135], v2
	ds_read_b128 v[136:139], v3
	s_add_i32 s42, s58, 31
	s_mov_b64 s[8:9], -1
	s_cmp_gt_i32 s42, s54
	s_waitcnt lgkmcnt(3)
	v_mfma_f32_32x32x16_bf16 v[96:111], v[6:9], v[116:119], 0
	s_waitcnt lgkmcnt(2)
	v_mfma_f32_32x32x16_bf16 v[96:111], v[10:13], v[120:123], v[96:111]
	v_add_u32_e32 v2, s58, v188
	s_waitcnt lgkmcnt(1)
	v_mfma_f32_32x32x16_bf16 v[96:111], v[132:135], v[124:127], v[96:111]
	s_waitcnt lgkmcnt(0)
	v_mfma_f32_32x32x16_bf16 v[96:111], v[136:139], v[128:131], v[96:111]
	s_cbranch_scc1 .LBB0_382
	s_nop 10
	v_fmamk_f32 v80, v96, 0x3e38aa3b, v216
	v_fma_f32 v81, v97, s30, -v214
	v_fmamk_f32 v82, v98, 0x3e38aa3b, v217
	v_max3_f32 v4, v80, s52, v81
	v_fmamk_f32 v83, v99, 0x3e38aa3b, v218
	v_fmamk_f32 v84, v100, 0x3e38aa3b, v219
	v_max3_f32 v4, v4, v82, v83
	v_fmamk_f32 v85, v101, 0x3e38aa3b, v220
	v_fmamk_f32 v86, v102, 0x3e38aa3b, v221
	v_max3_f32 v4, v4, v84, v85
	v_fmamk_f32 v87, v103, 0x3e38aa3b, v222
	v_cvt_f32_i32_e32 v3, v2
	v_fmamk_f32 v88, v104, 0x3e38aa3b, v223
	v_max3_f32 v4, v4, v86, v87
	v_fmamk_f32 v89, v105, 0x3e38aa3b, v224
	v_fmamk_f32 v90, v106, 0x3e38aa3b, v225
	v_max3_f32 v4, v4, v88, v89
	v_fmamk_f32 v91, v107, 0x3e38aa3b, v226
	v_fmamk_f32 v92, v108, 0x3e38aa3b, v227
	v_max3_f32 v4, v4, v90, v91
	v_fmamk_f32 v93, v109, 0x3e38aa3b, v228
	v_fmamk_f32 v94, v110, 0x3e38aa3b, v229
	v_max3_f32 v4, v4, v92, v93
	v_fmamk_f32 v95, v111, 0x3e38aa3b, v230
	v_mul_f32_e64 v3, -v214, v3
	v_max3_f32 v4, v4, v94, v95
	s_mov_b64 s[8:9], 0
